# gemm_in/ffn_in tile order: two row pairs x 32 column tiles concurrently per XCD (A shared by 32 blocks)
# baseline (speedup 1.0000x reference)
.LBB0_209:
	s_not_b32 s2, s5
	s_add_i32 s2, s8, s2
	s_add_i32 s2, s2, s17
	s_ashr_i32 s3, s2, 31
	s_abs_i32 s2, s2
	s_mul_hi_u32 s5, s2, s72
	s_mul_i32 s8, s5, s4
	s_sub_i32 s2, s2, s8
	s_xor_b32 s3, s3, s16
	s_add_i32 s8, s5, 1
	s_sub_i32 s9, s2, s4
	s_cmp_ge_u32 s2, s4
	s_cselect_b32 s5, s8, s5
	s_cselect_b32 s2, s9, s2
	s_add_i32 s8, s5, 1
	s_cmp_ge_u32 s2, s4
	s_cselect_b32 s2, s8, s5
	s_xor_b32 s2, s2, s3
	s_sub_i32 s2, s2, s3
	s_add_i32 s3, s15, s24
	s_not_b32 s4, s23
	s_add_i32 s4, s4, s3
	s_ashr_i32 s3, s4, 31
	s_abs_i32 s4, s4
	s_mul_i32 s1, s4, s1
	s_mul_hi_u32 s0, s4, s0
	s_add_i32 s0, s0, s1
	s_mul_i32 s1, s0, s12
	s_sub_i32 s1, s4, s1
	s_xor_b32 s3, s3, s13
	s_add_i32 s4, s0, 1
	s_sub_i32 s5, s1, s12
	s_cmp_ge_u32 s1, s12
	s_cselect_b32 s0, s4, s0
	s_cselect_b32 s1, s5, s1
	s_add_i32 s4, s0, 1
	s_cmp_ge_u32 s1, s12
	s_cselect_b32 s0, s4, s0
	s_xor_b32 s0, s0, s3
	s_sub_i32 s3, s0, s3
	s_cmp_lt_i32 s22, 0
	s_cselect_b64 s[8:9], -1, 0
	s_and_b64 s[0:1], s[8:9], exec
	s_cselect_b32 s26, s3, s2
	s_not_b32 s0, s14
	s_lshr_b32 s0, s0, 31
	s_add_i32 s26, s26, s0
	s_cmp_lt_i32 s26, 1
	s_cbranch_scc1 .LBB0_476
	s_lshr_b32 s27, s10, 3
	s_cmp_lt_i32 s14, 0
	s_mul_hi_u32 s0, s14, 0x3521cfb3
	s_cselect_b64 s[10:11], -1, 0
	s_sub_i32 s2, s14, s0
	s_lshr_b32 s2, s2, 1
	s_add_i32 s2, s2, s0
	s_lshr_b32 s0, s2, 5
	s_add_i32 s28, s0, 0x80
	s_mul_i32 s0, s0, 53
	v_and_b32_e32 v2, 15, v0
	s_sub_i32 s29, s14, s0
	v_ashrrev_i32_e32 v3, 1, v0
	s_movk_i32 s0, 0xffc0
	v_and_or_b32 v87, v3, s0, v2
	v_lshrrev_b32_e32 v2, 2, v0
	v_and_b32_e32 v2, 12, v2
	v_and_or_b32 v86, v0, 64, v2
	v_and_b32_e32 v0, 64, v0
	v_cmp_ne_u32_e64 s[40:41], 0, v0
	v_or_b32_e32 v0, 16, v86
	v_cmp_gt_u32_e64 s[44:45], 40, v0
	v_or_b32_e32 v0, 32, v86
	v_cmp_gt_u32_e64 s[4:5], 40, v0
	v_cvt_f32_u32_e32 v0, s25
	v_readlane_b32 s2, v249, 52
	s_load_dwordx2 s[12:13], s[6:7], 0x138
	s_load_dwordx2 s[14:15], s[6:7], 0xe0
	s_lshl_b32 s0, s2, 8
	v_rcp_iflag_f32_e32 v0, v0
	s_or_b32 s30, s0, 0xffffc000
	s_sub_i32 s0, 0, s25
	s_mov_b32 s18, s2
	v_mul_f32_e32 v0, 0x4f7ffffe, v0
	v_cvt_u32_f32_e32 v0, v0
	v_readlane_b32 s3, v249, 53
	s_mul_i32 s72, s2, 0xc00
	s_lshl_b32 s31, s2, 14
	v_readfirstlane_b32 s16, v0
	s_mul_i32 s0, s0, s16
	s_mul_hi_u32 s0, s16, s0
	s_lshl_b32 s2, s2, 6
	s_add_i32 s33, s16, s0
	s_mul_i32 s16, s18, 0xd40000
	s_mov_b32 s3, s73
	s_mul_hi_u32 s0, s18, 0xd40000
	s_waitcnt lgkmcnt(0)
	s_add_u32 s34, s14, s16
	s_mov_b32 s1, 0
	v_or_b32_e32 v104, 0xfffff180, v86
	v_cmp_gt_u32_e64 s[42:43], 40, v86
	s_addc_u32 s35, s15, s0
	s_lshl_b64 s[16:17], s[72:73], 2
	s_lshl_b64 s[18:19], s[2:3], 2
	v_lshlrev_b32_e32 v105, 2, v2
	s_mov_b32 s32, 0
	v_readlane_b32 s2, v249, 1
	s_nop 0
	s_cmpk_lg_u32 s2, 0x200
	s_cbranch_scc1 .LBB0_212
	s_mov_b32 s48, 0
	v_readlane_b32 s2, v249, 0
	s_nop 0
	s_and_b32 s3, s2, 7
	s_lshr_b32 s2, s2, 3
	s_cmp_lt_u32 s2, 40
	s_cselect_b32 s38, 7, 6
	s_cmp_lt_u32 s48, s38
	s_cbranch_scc0 .Lg2_c0_extra
	s_lshl_b32 s20, s48, 6
	s_add_i32 s20, s20, s2
	s_mov_b32 s21, 0
	s_cmp_ge_u32 s20, 0x6a
	s_addc_u32 s21, s21, 0
	s_cmp_ge_u32 s20, 0xd4
	s_addc_u32 s21, s21, 0
	s_cmp_ge_u32 s20, 0x13e
	s_addc_u32 s21, s21, 0
	s_mul_i32 s0, s21, 0x6a
	s_sub_i32 s20, s20, s0
	s_lshr_b32 s37, s20, 1
	s_and_b32 s20, s20, 1
	s_lshl_b32 s21, s21, 2
	s_add_i32 s20, s20, s21
	s_lshl_b32 s20, s20, 3
	s_add_i32 s0, s20, s3
	s_add_i32 s49, s0, 16
	s_branch .Lg2_c0_have

.Lg2_k:
	s_waitcnt vmcnt(0)
	s_barrier
	s_add_i32 m0, s58, 0xc000
	s_nop 0
	global_load_lds_dwordx4 v74, s[56:57]
	s_add_i32 m0, s58, 0xd000
	s_nop 0
	global_load_lds_dwordx4 v75, s[56:57]
	s_add_i32 m0, s58, 0xe000
	s_nop 0
	global_load_lds_dwordx4 v76, s[56:57]
	s_add_i32 m0, s58, 0xf000
	s_nop 0
	global_load_lds_dwordx4 v77, s[56:57]
	s_add_u32 s56, s56, 0x80
	s_addc_u32 s57, s57, 0
	ds_read_b128 v[148:151], v78 offset:0
	ds_read_b128 v[152:155], v78 offset:2048
	ds_read_b128 v[156:159], v78 offset:4096
	ds_read_b128 v[160:163], v78 offset:6144
	ds_read_b128 v[188:191], v79 offset:32768
	ds_read_b128 v[192:195], v79 offset:34816
	ds_read_b128 v[208:211], v79 offset:36864
	ds_read_b128 v[212:215], v79 offset:38912
	ds_read_b128 v[164:167], v78 offset:16384
	ds_read_b128 v[168:171], v78 offset:18432
	ds_read_b128 v[174:177], v78 offset:20480
	ds_read_b128 v[182:185], v78 offset:22528
	s_setprio 1
	s_waitcnt lgkmcnt(4)
	v_mfma_f32_16x16x32_bf16 v[62:65], v[188:191], v[148:151], v[62:65]
	v_mfma_f32_16x16x32_bf16 v[58:61], v[192:195], v[148:151], v[58:61]
	v_mfma_f32_16x16x32_bf16 v[54:57], v[208:211], v[148:151], v[54:57]
	v_mfma_f32_16x16x32_bf16 v[50:53], v[212:215], v[148:151], v[50:53]
	v_mfma_f32_16x16x32_bf16 v[46:49], v[188:191], v[152:155], v[46:49]
	v_mfma_f32_16x16x32_bf16 v[42:45], v[192:195], v[152:155], v[42:45]
	v_mfma_f32_16x16x32_bf16 v[38:41], v[208:211], v[152:155], v[38:41]
	v_mfma_f32_16x16x32_bf16 v[34:37], v[212:215], v[152:155], v[34:37]
	v_mfma_f32_16x16x32_bf16 v[30:33], v[188:191], v[156:159], v[30:33]
	v_mfma_f32_16x16x32_bf16 v[26:29], v[192:195], v[156:159], v[26:29]
	v_mfma_f32_16x16x32_bf16 v[22:25], v[208:211], v[156:159], v[22:25]
	v_mfma_f32_16x16x32_bf16 v[18:21], v[212:215], v[156:159], v[18:21]
	v_mfma_f32_16x16x32_bf16 v[14:17], v[188:191], v[160:163], v[14:17]
	v_mfma_f32_16x16x32_bf16 v[10:13], v[192:195], v[160:163], v[10:13]
	v_mfma_f32_16x16x32_bf16 v[6:9], v[208:211], v[160:163], v[6:9]
	v_mfma_f32_16x16x32_bf16 v[2:5], v[212:215], v[160:163], v[2:5]
	s_waitcnt lgkmcnt(0)
	v_mfma_f32_16x16x32_bf16 v[66:69], v[188:191], v[164:167], v[66:69]
	v_mfma_f32_16x16x32_bf16 v[70:73], v[192:195], v[164:167], v[70:73]
	v_mfma_f32_16x16x32_bf16 v[82:85], v[208:211], v[164:167], v[82:85]
	v_mfma_f32_16x16x32_bf16 v[88:91], v[212:215], v[164:167], v[88:91]
	v_mfma_f32_16x16x32_bf16 v[92:95], v[188:191], v[168:171], v[92:95]
	v_mfma_f32_16x16x32_bf16 v[96:99], v[192:195], v[168:171], v[96:99]
	v_mfma_f32_16x16x32_bf16 v[100:103], v[208:211], v[168:171], v[100:103]
	v_mfma_f32_16x16x32_bf16 v[106:109], v[212:215], v[168:171], v[106:109]
	v_mfma_f32_16x16x32_bf16 v[110:113], v[188:191], v[174:177], v[110:113]
	v_mfma_f32_16x16x32_bf16 v[114:117], v[192:195], v[174:177], v[114:117]
	v_mfma_f32_16x16x32_bf16 v[118:121], v[208:211], v[174:177], v[118:121]
	v_mfma_f32_16x16x32_bf16 v[122:125], v[212:215], v[174:177], v[122:125]
	v_mfma_f32_16x16x32_bf16 v[126:129], v[188:191], v[182:185], v[126:129]
	v_mfma_f32_16x16x32_bf16 v[136:139], v[192:195], v[182:185], v[136:139]
	v_mfma_f32_16x16x32_bf16 v[140:143], v[208:211], v[182:185], v[140:143]
	v_mfma_f32_16x16x32_bf16 v[144:147], v[212:215], v[182:185], v[144:147]
	s_setprio 0
	ds_read_b128 v[148:151], v80 offset:0
	ds_read_b128 v[152:155], v80 offset:2048
	ds_read_b128 v[156:159], v80 offset:4096
	ds_read_b128 v[160:163], v80 offset:6144
	ds_read_b128 v[188:191], v81 offset:32768
	ds_read_b128 v[192:195], v81 offset:34816
	ds_read_b128 v[208:211], v81 offset:36864
	ds_read_b128 v[212:215], v81 offset:38912
	ds_read_b128 v[164:167], v80 offset:16384
	ds_read_b128 v[168:171], v80 offset:18432
	ds_read_b128 v[174:177], v80 offset:20480
	ds_read_b128 v[182:185], v80 offset:22528
	s_waitcnt lgkmcnt(0)
	s_barrier
	s_add_i32 m0, s58, 0x0
	s_nop 0
	global_load_lds_dwordx4 v74, s[50:51]
	s_add_i32 m0, s58, 0x1000
	s_nop 0
	global_load_lds_dwordx4 v75, s[50:51]
	s_add_i32 m0, s58, 0x2000
	s_nop 0
	global_load_lds_dwordx4 v76, s[50:51]
	s_add_i32 m0, s58, 0x3000
	s_nop 0
	global_load_lds_dwordx4 v77, s[50:51]
	s_add_i32 m0, s58, 0x4000
	s_nop 0
	global_load_lds_dwordx4 v74, s[52:53]
	s_add_i32 m0, s58, 0x5000
	s_nop 0
	global_load_lds_dwordx4 v75, s[52:53]
	s_add_i32 m0, s58, 0x6000
	s_nop 0
	global_load_lds_dwordx4 v76, s[52:53]
	s_add_i32 m0, s58, 0x7000
	s_nop 0
	global_load_lds_dwordx4 v77, s[52:53]
	s_add_u32 s50, s50, 0x80
	s_addc_u32 s51, s51, 0
	s_add_u32 s52, s52, 0x80
	s_addc_u32 s53, s53, 0
	s_setprio 1
	v_mfma_f32_16x16x32_bf16 v[62:65], v[188:191], v[148:151], v[62:65]
	v_mfma_f32_16x16x32_bf16 v[58:61], v[192:195], v[148:151], v[58:61]
	v_mfma_f32_16x16x32_bf16 v[54:57], v[208:211], v[148:151], v[54:57]
	v_mfma_f32_16x16x32_bf16 v[50:53], v[212:215], v[148:151], v[50:53]
	v_mfma_f32_16x16x32_bf16 v[46:49], v[188:191], v[152:155], v[46:49]
	v_mfma_f32_16x16x32_bf16 v[42:45], v[192:195], v[152:155], v[42:45]
	v_mfma_f32_16x16x32_bf16 v[38:41], v[208:211], v[152:155], v[38:41]
	v_mfma_f32_16x16x32_bf16 v[34:37], v[212:215], v[152:155], v[34:37]
	v_mfma_f32_16x16x32_bf16 v[30:33], v[188:191], v[156:159], v[30:33]
	v_mfma_f32_16x16x32_bf16 v[26:29], v[192:195], v[156:159], v[26:29]
	v_mfma_f32_16x16x32_bf16 v[22:25], v[208:211], v[156:159], v[22:25]
	v_mfma_f32_16x16x32_bf16 v[18:21], v[212:215], v[156:159], v[18:21]
	v_mfma_f32_16x16x32_bf16 v[14:17], v[188:191], v[160:163], v[14:17]
	v_mfma_f32_16x16x32_bf16 v[10:13], v[192:195], v[160:163], v[10:13]
	v_mfma_f32_16x16x32_bf16 v[6:9], v[208:211], v[160:163], v[6:9]
	v_mfma_f32_16x16x32_bf16 v[2:5], v[212:215], v[160:163], v[2:5]
	v_mfma_f32_16x16x32_bf16 v[66:69], v[188:191], v[164:167], v[66:69]
	v_mfma_f32_16x16x32_bf16 v[70:73], v[192:195], v[164:167], v[70:73]
	v_mfma_f32_16x16x32_bf16 v[82:85], v[208:211], v[164:167], v[82:85]
	v_mfma_f32_16x16x32_bf16 v[88:91], v[212:215], v[164:167], v[88:91]
	v_mfma_f32_16x16x32_bf16 v[92:95], v[188:191], v[168:171], v[92:95]
	v_mfma_f32_16x16x32_bf16 v[96:99], v[192:195], v[168:171], v[96:99]
	v_mfma_f32_16x16x32_bf16 v[100:103], v[208:211], v[168:171], v[100:103]
	v_mfma_f32_16x16x32_bf16 v[106:109], v[212:215], v[168:171], v[106:109]
	v_mfma_f32_16x16x32_bf16 v[110:113], v[188:191], v[174:177], v[110:113]
	v_mfma_f32_16x16x32_bf16 v[114:117], v[192:195], v[174:177], v[114:117]
	v_mfma_f32_16x16x32_bf16 v[118:121], v[208:211], v[174:177], v[118:121]
	v_mfma_f32_16x16x32_bf16 v[122:125], v[212:215], v[174:177], v[122:125]
	v_mfma_f32_16x16x32_bf16 v[126:129], v[188:191], v[182:185], v[126:129]
	v_mfma_f32_16x16x32_bf16 v[136:139], v[192:195], v[182:185], v[136:139]
	v_mfma_f32_16x16x32_bf16 v[140:143], v[208:211], v[182:185], v[140:143]
	v_mfma_f32_16x16x32_bf16 v[144:147], v[212:215], v[182:185], v[144:147]
	s_setprio 0
	s_waitcnt vmcnt(0)
	s_barrier
	s_add_i32 m0, s58, 0x8000
	s_nop 0
	global_load_lds_dwordx4 v74, s[56:57]
	s_add_i32 m0, s58, 0x9000
	s_nop 0
	global_load_lds_dwordx4 v75, s[56:57]
	s_add_i32 m0, s58, 0xa000
	s_nop 0
	global_load_lds_dwordx4 v76, s[56:57]
	s_add_i32 m0, s58, 0xb000
	s_nop 0
	global_load_lds_dwordx4 v77, s[56:57]
	s_add_u32 s56, s56, 0x80
	s_addc_u32 s57, s57, 0
	ds_read_b128 v[148:151], v78 offset:0
	ds_read_b128 v[152:155], v78 offset:2048
	ds_read_b128 v[156:159], v78 offset:4096
	ds_read_b128 v[160:163], v78 offset:6144
	ds_read_b128 v[188:191], v79 offset:49152
	ds_read_b128 v[192:195], v79 offset:51200
	ds_read_b128 v[208:211], v79 offset:53248
	ds_read_b128 v[212:215], v79 offset:55296
	ds_read_b128 v[164:167], v78 offset:16384
	ds_read_b128 v[168:171], v78 offset:18432
	ds_read_b128 v[174:177], v78 offset:20480
	ds_read_b128 v[182:185], v78 offset:22528
	s_setprio 1
	s_waitcnt lgkmcnt(4)
	v_mfma_f32_16x16x32_bf16 v[62:65], v[188:191], v[148:151], v[62:65]
	v_mfma_f32_16x16x32_bf16 v[58:61], v[192:195], v[148:151], v[58:61]
	v_mfma_f32_16x16x32_bf16 v[54:57], v[208:211], v[148:151], v[54:57]
	v_mfma_f32_16x16x32_bf16 v[50:53], v[212:215], v[148:151], v[50:53]
	v_mfma_f32_16x16x32_bf16 v[46:49], v[188:191], v[152:155], v[46:49]
	v_mfma_f32_16x16x32_bf16 v[42:45], v[192:195], v[152:155], v[42:45]
	v_mfma_f32_16x16x32_bf16 v[38:41], v[208:211], v[152:155], v[38:41]
	v_mfma_f32_16x16x32_bf16 v[34:37], v[212:215], v[152:155], v[34:37]
	v_mfma_f32_16x16x32_bf16 v[30:33], v[188:191], v[156:159], v[30:33]
	v_mfma_f32_16x16x32_bf16 v[26:29], v[192:195], v[156:159], v[26:29]
	v_mfma_f32_16x16x32_bf16 v[22:25], v[208:211], v[156:159], v[22:25]
	v_mfma_f32_16x16x32_bf16 v[18:21], v[212:215], v[156:159], v[18:21]
	v_mfma_f32_16x16x32_bf16 v[14:17], v[188:191], v[160:163], v[14:17]
	v_mfma_f32_16x16x32_bf16 v[10:13], v[192:195], v[160:163], v[10:13]
	v_mfma_f32_16x16x32_bf16 v[6:9], v[208:211], v[160:163], v[6:9]
	v_mfma_f32_16x16x32_bf16 v[2:5], v[212:215], v[160:163], v[2:5]
	s_waitcnt lgkmcnt(0)
	v_mfma_f32_16x16x32_bf16 v[66:69], v[188:191], v[164:167], v[66:69]
	v_mfma_f32_16x16x32_bf16 v[70:73], v[192:195], v[164:167], v[70:73]
	v_mfma_f32_16x16x32_bf16 v[82:85], v[208:211], v[164:167], v[82:85]
	v_mfma_f32_16x16x32_bf16 v[88:91], v[212:215], v[164:167], v[88:91]
	v_mfma_f32_16x16x32_bf16 v[92:95], v[188:191], v[168:171], v[92:95]
	v_mfma_f32_16x16x32_bf16 v[96:99], v[192:195], v[168:171], v[96:99]
	v_mfma_f32_16x16x32_bf16 v[100:103], v[208:211], v[168:171], v[100:103]
	v_mfma_f32_16x16x32_bf16 v[106:109], v[212:215], v[168:171], v[106:109]
	v_mfma_f32_16x16x32_bf16 v[110:113], v[188:191], v[174:177], v[110:113]
	v_mfma_f32_16x16x32_bf16 v[114:117], v[192:195], v[174:177], v[114:117]
	v_mfma_f32_16x16x32_bf16 v[118:121], v[208:211], v[174:177], v[118:121]
	v_mfma_f32_16x16x32_bf16 v[122:125], v[212:215], v[174:177], v[122:125]
	v_mfma_f32_16x16x32_bf16 v[126:129], v[188:191], v[182:185], v[126:129]
	v_mfma_f32_16x16x32_bf16 v[136:139], v[192:195], v[182:185], v[136:139]
	v_mfma_f32_16x16x32_bf16 v[140:143], v[208:211], v[182:185], v[140:143]
	v_mfma_f32_16x16x32_bf16 v[144:147], v[212:215], v[182:185], v[144:147]
	s_setprio 0
	ds_read_b128 v[148:151], v80 offset:0
	ds_read_b128 v[152:155], v80 offset:2048
	ds_read_b128 v[156:159], v80 offset:4096
	ds_read_b128 v[160:163], v80 offset:6144
	ds_read_b128 v[188:191], v81 offset:49152
	ds_read_b128 v[192:195], v81 offset:51200
	ds_read_b128 v[208:211], v81 offset:53248
	ds_read_b128 v[212:215], v81 offset:55296
	ds_read_b128 v[164:167], v80 offset:16384
	ds_read_b128 v[168:171], v80 offset:18432
	ds_read_b128 v[174:177], v80 offset:20480
	ds_read_b128 v[182:185], v80 offset:22528
	s_waitcnt lgkmcnt(0)
	s_barrier
	s_add_i32 m0, s58, 0x0
	s_nop 0
	global_load_lds_dwordx4 v74, s[50:51]
	s_add_i32 m0, s58, 0x1000
	s_nop 0
	global_load_lds_dwordx4 v75, s[50:51]
	s_add_i32 m0, s58, 0x2000
	s_nop 0
	global_load_lds_dwordx4 v76, s[50:51]
	s_add_i32 m0, s58, 0x3000
	s_nop 0
	global_load_lds_dwordx4 v77, s[50:51]
	s_add_i32 m0, s58, 0x4000
	s_nop 0
	global_load_lds_dwordx4 v74, s[52:53]
	s_add_i32 m0, s58, 0x5000
	s_nop 0
	global_load_lds_dwordx4 v75, s[52:53]
	s_add_i32 m0, s58, 0x6000
	s_nop 0
	global_load_lds_dwordx4 v76, s[52:53]
	s_add_i32 m0, s58, 0x7000
	s_nop 0
	global_load_lds_dwordx4 v77, s[52:53]
	s_add_u32 s50, s50, 0x80
	s_addc_u32 s51, s51, 0
	s_add_u32 s52, s52, 0x80
	s_addc_u32 s53, s53, 0
	s_setprio 1
	v_mfma_f32_16x16x32_bf16 v[62:65], v[188:191], v[148:151], v[62:65]
	v_mfma_f32_16x16x32_bf16 v[58:61], v[192:195], v[148:151], v[58:61]
	v_mfma_f32_16x16x32_bf16 v[54:57], v[208:211], v[148:151], v[54:57]
	v_mfma_f32_16x16x32_bf16 v[50:53], v[212:215], v[148:151], v[50:53]
	v_mfma_f32_16x16x32_bf16 v[46:49], v[188:191], v[152:155], v[46:49]
	v_mfma_f32_16x16x32_bf16 v[42:45], v[192:195], v[152:155], v[42:45]
	v_mfma_f32_16x16x32_bf16 v[38:41], v[208:211], v[152:155], v[38:41]
	v_mfma_f32_16x16x32_bf16 v[34:37], v[212:215], v[152:155], v[34:37]
	v_mfma_f32_16x16x32_bf16 v[30:33], v[188:191], v[156:159], v[30:33]
	v_mfma_f32_16x16x32_bf16 v[26:29], v[192:195], v[156:159], v[26:29]
	v_mfma_f32_16x16x32_bf16 v[22:25], v[208:211], v[156:159], v[22:25]
	v_mfma_f32_16x16x32_bf16 v[18:21], v[212:215], v[156:159], v[18:21]
	v_mfma_f32_16x16x32_bf16 v[14:17], v[188:191], v[160:163], v[14:17]
	v_mfma_f32_16x16x32_bf16 v[10:13], v[192:195], v[160:163], v[10:13]
	v_mfma_f32_16x16x32_bf16 v[6:9], v[208:211], v[160:163], v[6:9]
	v_mfma_f32_16x16x32_bf16 v[2:5], v[212:215], v[160:163], v[2:5]
	v_mfma_f32_16x16x32_bf16 v[66:69], v[188:191], v[164:167], v[66:69]
	v_mfma_f32_16x16x32_bf16 v[70:73], v[192:195], v[164:167], v[70:73]
	v_mfma_f32_16x16x32_bf16 v[82:85], v[208:211], v[164:167], v[82:85]
	v_mfma_f32_16x16x32_bf16 v[88:91], v[212:215], v[164:167], v[88:91]
	v_mfma_f32_16x16x32_bf16 v[92:95], v[188:191], v[168:171], v[92:95]
	v_mfma_f32_16x16x32_bf16 v[96:99], v[192:195], v[168:171], v[96:99]
	v_mfma_f32_16x16x32_bf16 v[100:103], v[208:211], v[168:171], v[100:103]
	v_mfma_f32_16x16x32_bf16 v[106:109], v[212:215], v[168:171], v[106:109]
	v_mfma_f32_16x16x32_bf16 v[110:113], v[188:191], v[174:177], v[110:113]
	v_mfma_f32_16x16x32_bf16 v[114:117], v[192:195], v[174:177], v[114:117]
	v_mfma_f32_16x16x32_bf16 v[118:121], v[208:211], v[174:177], v[118:121]
	v_mfma_f32_16x16x32_bf16 v[122:125], v[212:215], v[174:177], v[122:125]
	v_mfma_f32_16x16x32_bf16 v[126:129], v[188:191], v[182:185], v[126:129]
	v_mfma_f32_16x16x32_bf16 v[136:139], v[192:195], v[182:185], v[136:139]
	v_mfma_f32_16x16x32_bf16 v[140:143], v[208:211], v[182:185], v[140:143]
	v_mfma_f32_16x16x32_bf16 v[144:147], v[212:215], v[182:185], v[144:147]
	s_setprio 0
	s_add_i32 s59, s59, -1
	s_cmp_lg_u32 s59, 0
	s_cbranch_scc1 .Lg2_k
	s_waitcnt vmcnt(0)
	s_barrier
	s_add_i32 m0, s58, 0xc000
	s_nop 0
	global_load_lds_dwordx4 v74, s[56:57]
	s_add_i32 m0, s58, 0xd000
	s_nop 0
	global_load_lds_dwordx4 v75, s[56:57]
	s_add_i32 m0, s58, 0xe000
	s_nop 0
	global_load_lds_dwordx4 v76, s[56:57]
	s_add_i32 m0, s58, 0xf000
	s_nop 0
	global_load_lds_dwordx4 v77, s[56:57]
	s_add_u32 s56, s56, 0x80
	s_addc_u32 s57, s57, 0
	ds_read_b128 v[148:151], v78 offset:0
	ds_read_b128 v[152:155], v78 offset:2048
	ds_read_b128 v[156:159], v78 offset:4096
	ds_read_b128 v[160:163], v78 offset:6144
	ds_read_b128 v[188:191], v79 offset:32768
	ds_read_b128 v[192:195], v79 offset:34816
	ds_read_b128 v[208:211], v79 offset:36864
	ds_read_b128 v[212:215], v79 offset:38912
	ds_read_b128 v[164:167], v78 offset:16384
	ds_read_b128 v[168:171], v78 offset:18432
	ds_read_b128 v[174:177], v78 offset:20480
	ds_read_b128 v[182:185], v78 offset:22528
	s_setprio 1
	s_waitcnt lgkmcnt(4)
	v_mfma_f32_16x16x32_bf16 v[62:65], v[188:191], v[148:151], v[62:65]
	v_mfma_f32_16x16x32_bf16 v[58:61], v[192:195], v[148:151], v[58:61]
	v_mfma_f32_16x16x32_bf16 v[54:57], v[208:211], v[148:151], v[54:57]
	v_mfma_f32_16x16x32_bf16 v[50:53], v[212:215], v[148:151], v[50:53]
	v_mfma_f32_16x16x32_bf16 v[46:49], v[188:191], v[152:155], v[46:49]
	v_mfma_f32_16x16x32_bf16 v[42:45], v[192:195], v[152:155], v[42:45]
	v_mfma_f32_16x16x32_bf16 v[38:41], v[208:211], v[152:155], v[38:41]
	v_mfma_f32_16x16x32_bf16 v[34:37], v[212:215], v[152:155], v[34:37]
	v_mfma_f32_16x16x32_bf16 v[30:33], v[188:191], v[156:159], v[30:33]
	v_mfma_f32_16x16x32_bf16 v[26:29], v[192:195], v[156:159], v[26:29]
	v_mfma_f32_16x16x32_bf16 v[22:25], v[208:211], v[156:159], v[22:25]
	v_mfma_f32_16x16x32_bf16 v[18:21], v[212:215], v[156:159], v[18:21]
	v_mfma_f32_16x16x32_bf16 v[14:17], v[188:191], v[160:163], v[14:17]
	v_mfma_f32_16x16x32_bf16 v[10:13], v[192:195], v[160:163], v[10:13]
	v_mfma_f32_16x16x32_bf16 v[6:9], v[208:211], v[160:163], v[6:9]
	v_mfma_f32_16x16x32_bf16 v[2:5], v[212:215], v[160:163], v[2:5]
	s_waitcnt lgkmcnt(0)
	v_mfma_f32_16x16x32_bf16 v[66:69], v[188:191], v[164:167], v[66:69]
	v_mfma_f32_16x16x32_bf16 v[70:73], v[192:195], v[164:167], v[70:73]
	v_mfma_f32_16x16x32_bf16 v[82:85], v[208:211], v[164:167], v[82:85]
	v_mfma_f32_16x16x32_bf16 v[88:91], v[212:215], v[164:167], v[88:91]
	v_mfma_f32_16x16x32_bf16 v[92:95], v[188:191], v[168:171], v[92:95]
	v_mfma_f32_16x16x32_bf16 v[96:99], v[192:195], v[168:171], v[96:99]
	v_mfma_f32_16x16x32_bf16 v[100:103], v[208:211], v[168:171], v[100:103]
	v_mfma_f32_16x16x32_bf16 v[106:109], v[212:215], v[168:171], v[106:109]
	v_mfma_f32_16x16x32_bf16 v[110:113], v[188:191], v[174:177], v[110:113]
	v_mfma_f32_16x16x32_bf16 v[114:117], v[192:195], v[174:177], v[114:117]
	v_mfma_f32_16x16x32_bf16 v[118:121], v[208:211], v[174:177], v[118:121]
	v_mfma_f32_16x16x32_bf16 v[122:125], v[212:215], v[174:177], v[122:125]
	v_mfma_f32_16x16x32_bf16 v[126:129], v[188:191], v[182:185], v[126:129]
	v_mfma_f32_16x16x32_bf16 v[136:139], v[192:195], v[182:185], v[136:139]
	v_mfma_f32_16x16x32_bf16 v[140:143], v[208:211], v[182:185], v[140:143]
	v_mfma_f32_16x16x32_bf16 v[144:147], v[212:215], v[182:185], v[144:147]
	s_setprio 0
	ds_read_b128 v[148:151], v80 offset:0
	ds_read_b128 v[152:155], v80 offset:2048
	ds_read_b128 v[156:159], v80 offset:4096
	ds_read_b128 v[160:163], v80 offset:6144
	ds_read_b128 v[188:191], v81 offset:32768
	ds_read_b128 v[192:195], v81 offset:34816
	ds_read_b128 v[208:211], v81 offset:36864
	ds_read_b128 v[212:215], v81 offset:38912
	ds_read_b128 v[164:167], v80 offset:16384
	ds_read_b128 v[168:171], v80 offset:18432
	ds_read_b128 v[174:177], v80 offset:20480
	ds_read_b128 v[182:185], v80 offset:22528
	s_waitcnt lgkmcnt(0)
	s_barrier
	s_add_i32 m0, s58, 0x0
	s_nop 0
	global_load_lds_dwordx4 v74, s[50:51]
	s_add_i32 m0, s58, 0x1000
	s_nop 0
	global_load_lds_dwordx4 v75, s[50:51]
	s_add_i32 m0, s58, 0x2000
	s_nop 0
	global_load_lds_dwordx4 v76, s[50:51]
	s_add_i32 m0, s58, 0x3000
	s_nop 0
	global_load_lds_dwordx4 v77, s[50:51]
	s_add_i32 m0, s58, 0x4000
	s_nop 0
	global_load_lds_dwordx4 v74, s[52:53]
	s_add_i32 m0, s58, 0x5000
	s_nop 0
	global_load_lds_dwordx4 v75, s[52:53]
	s_add_i32 m0, s58, 0x6000
	s_nop 0
	global_load_lds_dwordx4 v76, s[52:53]
	s_add_i32 m0, s58, 0x7000
	s_nop 0
	global_load_lds_dwordx4 v77, s[52:53]
	s_add_u32 s50, s50, 0x80
	s_addc_u32 s51, s51, 0
	s_add_u32 s52, s52, 0x80
	s_addc_u32 s53, s53, 0
	s_setprio 1
	v_mfma_f32_16x16x32_bf16 v[62:65], v[188:191], v[148:151], v[62:65]
	v_mfma_f32_16x16x32_bf16 v[58:61], v[192:195], v[148:151], v[58:61]
	v_mfma_f32_16x16x32_bf16 v[54:57], v[208:211], v[148:151], v[54:57]
	v_mfma_f32_16x16x32_bf16 v[50:53], v[212:215], v[148:151], v[50:53]
	v_mfma_f32_16x16x32_bf16 v[46:49], v[188:191], v[152:155], v[46:49]
	v_mfma_f32_16x16x32_bf16 v[42:45], v[192:195], v[152:155], v[42:45]
	v_mfma_f32_16x16x32_bf16 v[38:41], v[208:211], v[152:155], v[38:41]
	v_mfma_f32_16x16x32_bf16 v[34:37], v[212:215], v[152:155], v[34:37]
	v_mfma_f32_16x16x32_bf16 v[30:33], v[188:191], v[156:159], v[30:33]
	v_mfma_f32_16x16x32_bf16 v[26:29], v[192:195], v[156:159], v[26:29]
	v_mfma_f32_16x16x32_bf16 v[22:25], v[208:211], v[156:159], v[22:25]
	v_mfma_f32_16x16x32_bf16 v[18:21], v[212:215], v[156:159], v[18:21]
	v_mfma_f32_16x16x32_bf16 v[14:17], v[188:191], v[160:163], v[14:17]
	v_mfma_f32_16x16x32_bf16 v[10:13], v[192:195], v[160:163], v[10:13]
	v_mfma_f32_16x16x32_bf16 v[6:9], v[208:211], v[160:163], v[6:9]
	v_mfma_f32_16x16x32_bf16 v[2:5], v[212:215], v[160:163], v[2:5]
	v_mfma_f32_16x16x32_bf16 v[66:69], v[188:191], v[164:167], v[66:69]
	v_mfma_f32_16x16x32_bf16 v[70:73], v[192:195], v[164:167], v[70:73]
	v_mfma_f32_16x16x32_bf16 v[82:85], v[208:211], v[164:167], v[82:85]
	v_mfma_f32_16x16x32_bf16 v[88:91], v[212:215], v[164:167], v[88:91]
	v_mfma_f32_16x16x32_bf16 v[92:95], v[188:191], v[168:171], v[92:95]
	v_mfma_f32_16x16x32_bf16 v[96:99], v[192:195], v[168:171], v[96:99]
	v_mfma_f32_16x16x32_bf16 v[100:103], v[208:211], v[168:171], v[100:103]
	v_mfma_f32_16x16x32_bf16 v[106:109], v[212:215], v[168:171], v[106:109]
	v_mfma_f32_16x16x32_bf16 v[110:113], v[188:191], v[174:177], v[110:113]
	v_mfma_f32_16x16x32_bf16 v[114:117], v[192:195], v[174:177], v[114:117]
	v_mfma_f32_16x16x32_bf16 v[118:121], v[208:211], v[174:177], v[118:121]
	v_mfma_f32_16x16x32_bf16 v[122:125], v[212:215], v[174:177], v[122:125]
	v_mfma_f32_16x16x32_bf16 v[126:129], v[188:191], v[182:185], v[126:129]
	v_mfma_f32_16x16x32_bf16 v[136:139], v[192:195], v[182:185], v[136:139]
	v_mfma_f32_16x16x32_bf16 v[140:143], v[208:211], v[182:185], v[140:143]
	v_mfma_f32_16x16x32_bf16 v[144:147], v[212:215], v[182:185], v[144:147]
	s_setprio 0
	s_waitcnt vmcnt(0)
	s_barrier
	ds_read_b128 v[148:151], v78 offset:0
	ds_read_b128 v[152:155], v78 offset:2048
	ds_read_b128 v[156:159], v78 offset:4096
	ds_read_b128 v[160:163], v78 offset:6144
	ds_read_b128 v[188:191], v79 offset:49152
	ds_read_b128 v[192:195], v79 offset:51200
	ds_read_b128 v[208:211], v79 offset:53248
	ds_read_b128 v[212:215], v79 offset:55296
	ds_read_b128 v[164:167], v78 offset:16384
	ds_read_b128 v[168:171], v78 offset:18432
	ds_read_b128 v[174:177], v78 offset:20480
	ds_read_b128 v[182:185], v78 offset:22528
	s_setprio 1
	s_waitcnt lgkmcnt(4)
	v_mfma_f32_16x16x32_bf16 v[62:65], v[188:191], v[148:151], v[62:65]
	v_mfma_f32_16x16x32_bf16 v[58:61], v[192:195], v[148:151], v[58:61]
	v_mfma_f32_16x16x32_bf16 v[54:57], v[208:211], v[148:151], v[54:57]
	v_mfma_f32_16x16x32_bf16 v[50:53], v[212:215], v[148:151], v[50:53]
	v_mfma_f32_16x16x32_bf16 v[46:49], v[188:191], v[152:155], v[46:49]
	v_mfma_f32_16x16x32_bf16 v[42:45], v[192:195], v[152:155], v[42:45]
	v_mfma_f32_16x16x32_bf16 v[38:41], v[208:211], v[152:155], v[38:41]
	v_mfma_f32_16x16x32_bf16 v[34:37], v[212:215], v[152:155], v[34:37]
	v_mfma_f32_16x16x32_bf16 v[30:33], v[188:191], v[156:159], v[30:33]
	v_mfma_f32_16x16x32_bf16 v[26:29], v[192:195], v[156:159], v[26:29]
	v_mfma_f32_16x16x32_bf16 v[22:25], v[208:211], v[156:159], v[22:25]
	v_mfma_f32_16x16x32_bf16 v[18:21], v[212:215], v[156:159], v[18:21]
	v_mfma_f32_16x16x32_bf16 v[14:17], v[188:191], v[160:163], v[14:17]
	v_mfma_f32_16x16x32_bf16 v[10:13], v[192:195], v[160:163], v[10:13]
	v_mfma_f32_16x16x32_bf16 v[6:9], v[208:211], v[160:163], v[6:9]
	v_mfma_f32_16x16x32_bf16 v[2:5], v[212:215], v[160:163], v[2:5]
	s_waitcnt lgkmcnt(0)
	v_mfma_f32_16x16x32_bf16 v[66:69], v[188:191], v[164:167], v[66:69]
	v_mfma_f32_16x16x32_bf16 v[70:73], v[192:195], v[164:167], v[70:73]
	v_mfma_f32_16x16x32_bf16 v[82:85], v[208:211], v[164:167], v[82:85]
	v_mfma_f32_16x16x32_bf16 v[88:91], v[212:215], v[164:167], v[88:91]
	v_mfma_f32_16x16x32_bf16 v[92:95], v[188:191], v[168:171], v[92:95]
	v_mfma_f32_16x16x32_bf16 v[96:99], v[192:195], v[168:171], v[96:99]
	v_mfma_f32_16x16x32_bf16 v[100:103], v[208:211], v[168:171], v[100:103]
	v_mfma_f32_16x16x32_bf16 v[106:109], v[212:215], v[168:171], v[106:109]
	v_mfma_f32_16x16x32_bf16 v[110:113], v[188:191], v[174:177], v[110:113]
	v_mfma_f32_16x16x32_bf16 v[114:117], v[192:195], v[174:177], v[114:117]
	v_mfma_f32_16x16x32_bf16 v[118:121], v[208:211], v[174:177], v[118:121]
	v_mfma_f32_16x16x32_bf16 v[122:125], v[212:215], v[174:177], v[122:125]
	v_mfma_f32_16x16x32_bf16 v[126:129], v[188:191], v[182:185], v[126:129]
	v_mfma_f32_16x16x32_bf16 v[136:139], v[192:195], v[182:185], v[136:139]
	v_mfma_f32_16x16x32_bf16 v[140:143], v[208:211], v[182:185], v[140:143]
	v_mfma_f32_16x16x32_bf16 v[144:147], v[212:215], v[182:185], v[144:147]
	s_setprio 0
	ds_read_b128 v[148:151], v80 offset:0
	ds_read_b128 v[152:155], v80 offset:2048
	ds_read_b128 v[156:159], v80 offset:4096
	ds_read_b128 v[160:163], v80 offset:6144
	ds_read_b128 v[188:191], v81 offset:49152
	ds_read_b128 v[192:195], v81 offset:51200
	ds_read_b128 v[208:211], v81 offset:53248
	ds_read_b128 v[212:215], v81 offset:55296
	ds_read_b128 v[164:167], v80 offset:16384
	ds_read_b128 v[168:171], v80 offset:18432
	ds_read_b128 v[174:177], v80 offset:20480
	ds_read_b128 v[182:185], v80 offset:22528
	s_setprio 1
	s_waitcnt lgkmcnt(4)
	v_mfma_f32_16x16x32_bf16 v[62:65], v[188:191], v[148:151], v[62:65]
	v_mfma_f32_16x16x32_bf16 v[58:61], v[192:195], v[148:151], v[58:61]
	v_mfma_f32_16x16x32_bf16 v[54:57], v[208:211], v[148:151], v[54:57]
	v_mfma_f32_16x16x32_bf16 v[50:53], v[212:215], v[148:151], v[50:53]
	v_mfma_f32_16x16x32_bf16 v[46:49], v[188:191], v[152:155], v[46:49]
	v_mfma_f32_16x16x32_bf16 v[42:45], v[192:195], v[152:155], v[42:45]
	v_mfma_f32_16x16x32_bf16 v[38:41], v[208:211], v[152:155], v[38:41]
	v_mfma_f32_16x16x32_bf16 v[34:37], v[212:215], v[152:155], v[34:37]
	v_mfma_f32_16x16x32_bf16 v[30:33], v[188:191], v[156:159], v[30:33]
	v_mfma_f32_16x16x32_bf16 v[26:29], v[192:195], v[156:159], v[26:29]
	v_mfma_f32_16x16x32_bf16 v[22:25], v[208:211], v[156:159], v[22:25]
	v_mfma_f32_16x16x32_bf16 v[18:21], v[212:215], v[156:159], v[18:21]
	v_mfma_f32_16x16x32_bf16 v[14:17], v[188:191], v[160:163], v[14:17]
	v_mfma_f32_16x16x32_bf16 v[10:13], v[192:195], v[160:163], v[10:13]
	v_mfma_f32_16x16x32_bf16 v[6:9], v[208:211], v[160:163], v[6:9]
	v_mfma_f32_16x16x32_bf16 v[2:5], v[212:215], v[160:163], v[2:5]
	s_waitcnt lgkmcnt(0)
	v_mfma_f32_16x16x32_bf16 v[66:69], v[188:191], v[164:167], v[66:69]
	v_mfma_f32_16x16x32_bf16 v[70:73], v[192:195], v[164:167], v[70:73]
	v_mfma_f32_16x16x32_bf16 v[82:85], v[208:211], v[164:167], v[82:85]
	v_mfma_f32_16x16x32_bf16 v[88:91], v[212:215], v[164:167], v[88:91]
	v_mfma_f32_16x16x32_bf16 v[92:95], v[188:191], v[168:171], v[92:95]
	v_mfma_f32_16x16x32_bf16 v[96:99], v[192:195], v[168:171], v[96:99]
	v_mfma_f32_16x16x32_bf16 v[100:103], v[208:211], v[168:171], v[100:103]
	v_mfma_f32_16x16x32_bf16 v[106:109], v[212:215], v[168:171], v[106:109]
	v_mfma_f32_16x16x32_bf16 v[110:113], v[188:191], v[174:177], v[110:113]
	v_mfma_f32_16x16x32_bf16 v[114:117], v[192:195], v[174:177], v[114:117]
	v_mfma_f32_16x16x32_bf16 v[118:121], v[208:211], v[174:177], v[118:121]
	v_mfma_f32_16x16x32_bf16 v[122:125], v[212:215], v[174:177], v[122:125]
	v_mfma_f32_16x16x32_bf16 v[126:129], v[188:191], v[182:185], v[126:129]
	v_mfma_f32_16x16x32_bf16 v[136:139], v[192:195], v[182:185], v[136:139]
	v_mfma_f32_16x16x32_bf16 v[140:143], v[208:211], v[182:185], v[140:143]
	v_mfma_f32_16x16x32_bf16 v[144:147], v[212:215], v[182:185], v[144:147]
	s_setprio 0
	s_nop 7
	s_nop 7
	s_nop 7
	v_mov_b32_e32 v148, v66
	v_mov_b32_e32 v149, v67
	v_mov_b32_e32 v150, v68
	v_mov_b32_e32 v151, v69
	v_mov_b32_e32 v152, v70
	v_mov_b32_e32 v153, v71
	v_mov_b32_e32 v154, v72
	v_mov_b32_e32 v155, v73
	v_mov_b32_e32 v156, v82
	v_mov_b32_e32 v157, v83
	v_mov_b32_e32 v158, v84
	v_mov_b32_e32 v159, v85
	v_mov_b32_e32 v160, v88
	v_mov_b32_e32 v161, v89
	v_mov_b32_e32 v162, v90
	v_mov_b32_e32 v163, v91
	v_mov_b32_e32 v164, v92
	v_mov_b32_e32 v165, v93
	v_mov_b32_e32 v166, v94
	v_mov_b32_e32 v167, v95
	v_mov_b32_e32 v168, v96
	v_mov_b32_e32 v169, v97
	v_mov_b32_e32 v170, v98
	v_mov_b32_e32 v171, v99
	v_mov_b32_e32 v174, v100
	v_mov_b32_e32 v175, v101
	v_mov_b32_e32 v176, v102
	v_mov_b32_e32 v177, v103
	v_mov_b32_e32 v182, v106
	v_mov_b32_e32 v183, v107
	v_mov_b32_e32 v184, v108
	v_mov_b32_e32 v185, v109
	v_mov_b32_e32 v188, v110
	v_mov_b32_e32 v189, v111
	v_mov_b32_e32 v190, v112
	v_mov_b32_e32 v191, v113
	v_mov_b32_e32 v192, v114
	v_mov_b32_e32 v193, v115
	v_mov_b32_e32 v194, v116
	v_mov_b32_e32 v195, v117
	v_mov_b32_e32 v208, v118
	v_mov_b32_e32 v209, v119
	v_mov_b32_e32 v210, v120
	v_mov_b32_e32 v211, v121
	v_mov_b32_e32 v212, v122
	v_mov_b32_e32 v213, v123
	v_mov_b32_e32 v214, v124
	v_mov_b32_e32 v215, v125
	v_mov_b32_e32 v216, v126
	v_mov_b32_e32 v217, v127
	v_mov_b32_e32 v218, v128
	v_mov_b32_e32 v219, v129
	v_mov_b32_e32 v220, v136
	v_mov_b32_e32 v221, v137
	v_mov_b32_e32 v222, v138
	v_mov_b32_e32 v223, v139
	v_mov_b32_e32 v242, v140
	v_mov_b32_e32 v243, v141
	v_mov_b32_e32 v244, v142
	v_mov_b32_e32 v245, v143
	v_mov_b32_e32 v199, v144
	v_mov_b32_e32 v206, v145
	v_mov_b32_e32 v207, v146
	v_mov_b32_e32 v226, v147
	s_add_i32 s48, s48, 1
	s_mov_b32 s65, 0
	v_readlane_b32 s2, v249, 0
	s_nop 0
	s_and_b32 s3, s2, 7
	s_lshr_b32 s2, s2, 3
	s_cmp_lt_u32 s2, 40
	s_cselect_b32 s38, 7, 6
	s_cmp_lt_u32 s48, s38
	s_cbranch_scc0 .Lg2_c1_extra
	s_lshl_b32 s20, s48, 6
	s_add_i32 s20, s20, s2
	s_mov_b32 s21, 0
	s_cmp_ge_u32 s20, 0x6a
	s_addc_u32 s21, s21, 0
	s_cmp_ge_u32 s20, 0xd4
	s_addc_u32 s21, s21, 0
	s_cmp_ge_u32 s20, 0x13e
	s_addc_u32 s21, s21, 0
	s_mul_i32 s60, s21, 0x6a
	s_sub_i32 s20, s20, s60
	s_lshr_b32 s61, s20, 1
	s_and_b32 s20, s20, 1
	s_lshl_b32 s21, s21, 2
	s_add_i32 s20, s20, s21
	s_lshl_b32 s20, s20, 3
	s_add_i32 s60, s20, s3
	s_add_i32 s64, s60, 16
	s_branch .Lg2_c1_have

.LBB0_2352:
	v_and_b32_e32 v2, 15, v0
	v_ashrrev_i32_e32 v3, 1, v0
	s_movk_i32 s8, 0xffc0
	s_waitcnt vmcnt(2)
	v_and_or_b32 v74, v3, s8, v2
	v_lshrrev_b32_e32 v2, 1, v0
	v_lshrrev_b32_e32 v0, 2, v0
	s_and_b32 s17, s2, 7
	v_and_b32_e32 v0, 12, v0
	v_and_or_b32 v75, v2, 32, v0
	v_cvt_f32_ubyte0_e32 v0, s17
	v_rcp_iflag_f32_e32 v0, v0
	s_lshr_b32 s16, s2, 3
	s_cmp_lt_i32 s12, 0
	s_cselect_b64 s[2:3], -1, 0
	v_mul_f32_e32 v0, 0x4f7ffffe, v0
	v_cvt_u32_f32_e32 v0, v0
	s_sub_i32 s8, 0, s17
	s_load_dwordx2 s[4:5], s[0:1], 0x108
	s_load_dwordx2 s[6:7], s[0:1], 0x138
	v_readfirstlane_b32 s9, v0
	s_mul_i32 s8, s8, s9
	s_mul_hi_u32 s8, s9, s8
	s_add_i32 s18, s9, s8
	v_readlane_b32 s8, v249, 52
	v_readlane_b32 s9, v249, 53
	s_mov_b32 s10, s8
	s_mul_i32 s9, s10, 0xb00000
	s_mul_hi_u32 s8, s8, 0xb00000
	s_waitcnt lgkmcnt(0)
	s_add_u32 s19, s4, s9
	s_addc_u32 s20, s5, s8
	s_waitcnt vmcnt(0)
	s_mov_b32 s32, 0
	v_readlane_b32 s30, v249, 1
	s_nop 0
	s_cmpk_lg_u32 s30, 0x200
	s_cbranch_scc1 .LBB0_2354
	s_mov_b32 s48, 0
	v_readlane_b32 s30, v249, 0
	s_nop 0
	s_and_b32 s31, s30, 7
	s_lshr_b32 s30, s30, 3
	s_cmp_lt_u32 s30, 32
	s_cselect_b32 s35, 6, 5
	s_cmp_lt_u32 s48, s35
	s_cbranch_scc0 .Lf2_c0_extra
	s_lshl_b32 s33, s48, 6
	s_add_i32 s33, s33, s30
	s_mov_b32 s34, 0
	s_cmp_ge_u32 s33, 0x58
	s_addc_u32 s34, s34, 0
	s_cmp_ge_u32 s33, 0xb0
	s_addc_u32 s34, s34, 0
	s_cmp_ge_u32 s33, 0x108
	s_addc_u32 s34, s34, 0
	s_mul_i32 s8, s34, 0x58
	s_sub_i32 s33, s33, s8
	s_lshr_b32 s21, s33, 1
	s_and_b32 s33, s33, 1
	s_lshl_b32 s34, s34, 2
	s_add_i32 s33, s33, s34
	s_lshl_b32 s33, s33, 3
	s_add_i32 s8, s33, s31
	s_add_i32 s49, s8, 16
	s_branch .Lf2_c0_have

.Lf2_k:
	s_waitcnt vmcnt(0)
	s_barrier
	s_add_i32 m0, s64, 0xc000
	s_nop 0
	global_load_lds_dwordx4 v76, s[58:59]
	s_add_i32 m0, s64, 0xd000
	s_nop 0
	global_load_lds_dwordx4 v77, s[58:59]
	s_add_i32 m0, s64, 0xe000
	s_nop 0
	global_load_lds_dwordx4 v78, s[58:59]
	s_add_i32 m0, s64, 0xf000
	s_nop 0
	global_load_lds_dwordx4 v79, s[58:59]
	s_add_u32 s58, s58, 0x80
	s_addc_u32 s59, s59, 0
	ds_read_b128 v[148:151], v80 offset:0
	ds_read_b128 v[152:155], v80 offset:2048
	ds_read_b128 v[156:159], v80 offset:4096
	ds_read_b128 v[160:163], v80 offset:6144
	ds_read_b128 v[188:191], v144 offset:32768
	ds_read_b128 v[192:195], v144 offset:34816
	ds_read_b128 v[208:211], v144 offset:36864
	ds_read_b128 v[212:215], v144 offset:38912
	ds_read_b128 v[164:167], v80 offset:16384
	ds_read_b128 v[168:171], v80 offset:18432
	ds_read_b128 v[174:177], v80 offset:20480
	ds_read_b128 v[182:185], v80 offset:22528
	s_setprio 1
	s_waitcnt lgkmcnt(4)
	v_mfma_f32_16x16x32_bf16 v[62:65], v[188:191], v[148:151], v[62:65]
	v_mfma_f32_16x16x32_bf16 v[54:57], v[192:195], v[148:151], v[54:57]
	v_mfma_f32_16x16x32_bf16 v[58:61], v[208:211], v[148:151], v[58:61]
	v_mfma_f32_16x16x32_bf16 v[50:53], v[212:215], v[148:151], v[50:53]
	v_mfma_f32_16x16x32_bf16 v[46:49], v[188:191], v[152:155], v[46:49]
	v_mfma_f32_16x16x32_bf16 v[38:41], v[192:195], v[152:155], v[38:41]
	v_mfma_f32_16x16x32_bf16 v[42:45], v[208:211], v[152:155], v[42:45]
	v_mfma_f32_16x16x32_bf16 v[34:37], v[212:215], v[152:155], v[34:37]
	v_mfma_f32_16x16x32_bf16 v[30:33], v[188:191], v[156:159], v[30:33]
	v_mfma_f32_16x16x32_bf16 v[22:25], v[192:195], v[156:159], v[22:25]
	v_mfma_f32_16x16x32_bf16 v[26:29], v[208:211], v[156:159], v[26:29]
	v_mfma_f32_16x16x32_bf16 v[18:21], v[212:215], v[156:159], v[18:21]
	v_mfma_f32_16x16x32_bf16 v[14:17], v[188:191], v[160:163], v[14:17]
	v_mfma_f32_16x16x32_bf16 v[6:9], v[192:195], v[160:163], v[6:9]
	v_mfma_f32_16x16x32_bf16 v[10:13], v[208:211], v[160:163], v[10:13]
	v_mfma_f32_16x16x32_bf16 v[2:5], v[212:215], v[160:163], v[2:5]
	s_waitcnt lgkmcnt(0)
	v_mfma_f32_16x16x32_bf16 v[66:69], v[188:191], v[164:167], v[66:69]
	v_mfma_f32_16x16x32_bf16 v[70:73], v[192:195], v[164:167], v[70:73]
	v_mfma_f32_16x16x32_bf16 v[82:85], v[208:211], v[164:167], v[82:85]
	v_mfma_f32_16x16x32_bf16 v[86:89], v[212:215], v[164:167], v[86:89]
	v_mfma_f32_16x16x32_bf16 v[90:93], v[188:191], v[168:171], v[90:93]
	v_mfma_f32_16x16x32_bf16 v[94:97], v[192:195], v[168:171], v[94:97]
	v_mfma_f32_16x16x32_bf16 v[98:101], v[208:211], v[168:171], v[98:101]
	v_mfma_f32_16x16x32_bf16 v[102:105], v[212:215], v[168:171], v[102:105]
	v_mfma_f32_16x16x32_bf16 v[106:109], v[188:191], v[174:177], v[106:109]
	v_mfma_f32_16x16x32_bf16 v[110:113], v[192:195], v[174:177], v[110:113]
	v_mfma_f32_16x16x32_bf16 v[114:117], v[208:211], v[174:177], v[114:117]
	v_mfma_f32_16x16x32_bf16 v[118:121], v[212:215], v[174:177], v[118:121]
	v_mfma_f32_16x16x32_bf16 v[122:125], v[188:191], v[182:185], v[122:125]
	v_mfma_f32_16x16x32_bf16 v[126:129], v[192:195], v[182:185], v[126:129]
	v_mfma_f32_16x16x32_bf16 v[136:139], v[208:211], v[182:185], v[136:139]
	v_mfma_f32_16x16x32_bf16 v[140:143], v[212:215], v[182:185], v[140:143]
	s_setprio 0
	ds_read_b128 v[148:151], v81 offset:0
	ds_read_b128 v[152:155], v81 offset:2048
	ds_read_b128 v[156:159], v81 offset:4096
	ds_read_b128 v[160:163], v81 offset:6144
	ds_read_b128 v[188:191], v145 offset:32768
	ds_read_b128 v[192:195], v145 offset:34816
	ds_read_b128 v[208:211], v145 offset:36864
	ds_read_b128 v[212:215], v145 offset:38912
	ds_read_b128 v[164:167], v81 offset:16384
	ds_read_b128 v[168:171], v81 offset:18432
	ds_read_b128 v[174:177], v81 offset:20480
	ds_read_b128 v[182:185], v81 offset:22528
	s_waitcnt lgkmcnt(0)
	s_barrier
	s_add_i32 m0, s64, 0x0
	s_nop 0
	global_load_lds_dwordx4 v76, s[50:51]
	s_add_i32 m0, s64, 0x1000
	s_nop 0
	global_load_lds_dwordx4 v77, s[50:51]
	s_add_i32 m0, s64, 0x2000
	s_nop 0
	global_load_lds_dwordx4 v78, s[50:51]
	s_add_i32 m0, s64, 0x3000
	s_nop 0
	global_load_lds_dwordx4 v79, s[50:51]
	s_add_i32 m0, s64, 0x4000
	s_nop 0
	global_load_lds_dwordx4 v76, s[52:53]
	s_add_i32 m0, s64, 0x5000
	s_nop 0
	global_load_lds_dwordx4 v77, s[52:53]
	s_add_i32 m0, s64, 0x6000
	s_nop 0
	global_load_lds_dwordx4 v78, s[52:53]
	s_add_i32 m0, s64, 0x7000
	s_nop 0
	global_load_lds_dwordx4 v79, s[52:53]
	s_add_u32 s50, s50, 0x80
	s_addc_u32 s51, s51, 0
	s_add_u32 s52, s52, 0x80
	s_addc_u32 s53, s53, 0
	s_setprio 1
	v_mfma_f32_16x16x32_bf16 v[62:65], v[188:191], v[148:151], v[62:65]
	v_mfma_f32_16x16x32_bf16 v[54:57], v[192:195], v[148:151], v[54:57]
	v_mfma_f32_16x16x32_bf16 v[58:61], v[208:211], v[148:151], v[58:61]
	v_mfma_f32_16x16x32_bf16 v[50:53], v[212:215], v[148:151], v[50:53]
	v_mfma_f32_16x16x32_bf16 v[46:49], v[188:191], v[152:155], v[46:49]
	v_mfma_f32_16x16x32_bf16 v[38:41], v[192:195], v[152:155], v[38:41]
	v_mfma_f32_16x16x32_bf16 v[42:45], v[208:211], v[152:155], v[42:45]
	v_mfma_f32_16x16x32_bf16 v[34:37], v[212:215], v[152:155], v[34:37]
	v_mfma_f32_16x16x32_bf16 v[30:33], v[188:191], v[156:159], v[30:33]
	v_mfma_f32_16x16x32_bf16 v[22:25], v[192:195], v[156:159], v[22:25]
	v_mfma_f32_16x16x32_bf16 v[26:29], v[208:211], v[156:159], v[26:29]
	v_mfma_f32_16x16x32_bf16 v[18:21], v[212:215], v[156:159], v[18:21]
	v_mfma_f32_16x16x32_bf16 v[14:17], v[188:191], v[160:163], v[14:17]
	v_mfma_f32_16x16x32_bf16 v[6:9], v[192:195], v[160:163], v[6:9]
	v_mfma_f32_16x16x32_bf16 v[10:13], v[208:211], v[160:163], v[10:13]
	v_mfma_f32_16x16x32_bf16 v[2:5], v[212:215], v[160:163], v[2:5]
	v_mfma_f32_16x16x32_bf16 v[66:69], v[188:191], v[164:167], v[66:69]
	v_mfma_f32_16x16x32_bf16 v[70:73], v[192:195], v[164:167], v[70:73]
	v_mfma_f32_16x16x32_bf16 v[82:85], v[208:211], v[164:167], v[82:85]
	v_mfma_f32_16x16x32_bf16 v[86:89], v[212:215], v[164:167], v[86:89]
	v_mfma_f32_16x16x32_bf16 v[90:93], v[188:191], v[168:171], v[90:93]
	v_mfma_f32_16x16x32_bf16 v[94:97], v[192:195], v[168:171], v[94:97]
	v_mfma_f32_16x16x32_bf16 v[98:101], v[208:211], v[168:171], v[98:101]
	v_mfma_f32_16x16x32_bf16 v[102:105], v[212:215], v[168:171], v[102:105]
	v_mfma_f32_16x16x32_bf16 v[106:109], v[188:191], v[174:177], v[106:109]
	v_mfma_f32_16x16x32_bf16 v[110:113], v[192:195], v[174:177], v[110:113]
	v_mfma_f32_16x16x32_bf16 v[114:117], v[208:211], v[174:177], v[114:117]
	v_mfma_f32_16x16x32_bf16 v[118:121], v[212:215], v[174:177], v[118:121]
	v_mfma_f32_16x16x32_bf16 v[122:125], v[188:191], v[182:185], v[122:125]
	v_mfma_f32_16x16x32_bf16 v[126:129], v[192:195], v[182:185], v[126:129]
	v_mfma_f32_16x16x32_bf16 v[136:139], v[208:211], v[182:185], v[136:139]
	v_mfma_f32_16x16x32_bf16 v[140:143], v[212:215], v[182:185], v[140:143]
	s_setprio 0
	s_waitcnt vmcnt(0)
	s_barrier
	s_add_i32 m0, s64, 0x8000
	s_nop 0
	global_load_lds_dwordx4 v76, s[58:59]
	s_add_i32 m0, s64, 0x9000
	s_nop 0
	global_load_lds_dwordx4 v77, s[58:59]
	s_add_i32 m0, s64, 0xa000
	s_nop 0
	global_load_lds_dwordx4 v78, s[58:59]
	s_add_i32 m0, s64, 0xb000
	s_nop 0
	global_load_lds_dwordx4 v79, s[58:59]
	s_add_u32 s58, s58, 0x80
	s_addc_u32 s59, s59, 0
	ds_read_b128 v[148:151], v80 offset:0
	ds_read_b128 v[152:155], v80 offset:2048
	ds_read_b128 v[156:159], v80 offset:4096
	ds_read_b128 v[160:163], v80 offset:6144
	ds_read_b128 v[188:191], v144 offset:49152
	ds_read_b128 v[192:195], v144 offset:51200
	ds_read_b128 v[208:211], v144 offset:53248
	ds_read_b128 v[212:215], v144 offset:55296
	ds_read_b128 v[164:167], v80 offset:16384
	ds_read_b128 v[168:171], v80 offset:18432
	ds_read_b128 v[174:177], v80 offset:20480
	ds_read_b128 v[182:185], v80 offset:22528
	s_setprio 1
	s_waitcnt lgkmcnt(4)
	v_mfma_f32_16x16x32_bf16 v[62:65], v[188:191], v[148:151], v[62:65]
	v_mfma_f32_16x16x32_bf16 v[54:57], v[192:195], v[148:151], v[54:57]
	v_mfma_f32_16x16x32_bf16 v[58:61], v[208:211], v[148:151], v[58:61]
	v_mfma_f32_16x16x32_bf16 v[50:53], v[212:215], v[148:151], v[50:53]
	v_mfma_f32_16x16x32_bf16 v[46:49], v[188:191], v[152:155], v[46:49]
	v_mfma_f32_16x16x32_bf16 v[38:41], v[192:195], v[152:155], v[38:41]
	v_mfma_f32_16x16x32_bf16 v[42:45], v[208:211], v[152:155], v[42:45]
	v_mfma_f32_16x16x32_bf16 v[34:37], v[212:215], v[152:155], v[34:37]
	v_mfma_f32_16x16x32_bf16 v[30:33], v[188:191], v[156:159], v[30:33]
	v_mfma_f32_16x16x32_bf16 v[22:25], v[192:195], v[156:159], v[22:25]
	v_mfma_f32_16x16x32_bf16 v[26:29], v[208:211], v[156:159], v[26:29]
	v_mfma_f32_16x16x32_bf16 v[18:21], v[212:215], v[156:159], v[18:21]
	v_mfma_f32_16x16x32_bf16 v[14:17], v[188:191], v[160:163], v[14:17]
	v_mfma_f32_16x16x32_bf16 v[6:9], v[192:195], v[160:163], v[6:9]
	v_mfma_f32_16x16x32_bf16 v[10:13], v[208:211], v[160:163], v[10:13]
	v_mfma_f32_16x16x32_bf16 v[2:5], v[212:215], v[160:163], v[2:5]
	s_waitcnt lgkmcnt(0)
	v_mfma_f32_16x16x32_bf16 v[66:69], v[188:191], v[164:167], v[66:69]
	v_mfma_f32_16x16x32_bf16 v[70:73], v[192:195], v[164:167], v[70:73]
	v_mfma_f32_16x16x32_bf16 v[82:85], v[208:211], v[164:167], v[82:85]
	v_mfma_f32_16x16x32_bf16 v[86:89], v[212:215], v[164:167], v[86:89]
	v_mfma_f32_16x16x32_bf16 v[90:93], v[188:191], v[168:171], v[90:93]
	v_mfma_f32_16x16x32_bf16 v[94:97], v[192:195], v[168:171], v[94:97]
	v_mfma_f32_16x16x32_bf16 v[98:101], v[208:211], v[168:171], v[98:101]
	v_mfma_f32_16x16x32_bf16 v[102:105], v[212:215], v[168:171], v[102:105]
	v_mfma_f32_16x16x32_bf16 v[106:109], v[188:191], v[174:177], v[106:109]
	v_mfma_f32_16x16x32_bf16 v[110:113], v[192:195], v[174:177], v[110:113]
	v_mfma_f32_16x16x32_bf16 v[114:117], v[208:211], v[174:177], v[114:117]
	v_mfma_f32_16x16x32_bf16 v[118:121], v[212:215], v[174:177], v[118:121]
	v_mfma_f32_16x16x32_bf16 v[122:125], v[188:191], v[182:185], v[122:125]
	v_mfma_f32_16x16x32_bf16 v[126:129], v[192:195], v[182:185], v[126:129]
	v_mfma_f32_16x16x32_bf16 v[136:139], v[208:211], v[182:185], v[136:139]
	v_mfma_f32_16x16x32_bf16 v[140:143], v[212:215], v[182:185], v[140:143]
	s_setprio 0
	ds_read_b128 v[148:151], v81 offset:0
	ds_read_b128 v[152:155], v81 offset:2048
	ds_read_b128 v[156:159], v81 offset:4096
	ds_read_b128 v[160:163], v81 offset:6144
	ds_read_b128 v[188:191], v145 offset:49152
	ds_read_b128 v[192:195], v145 offset:51200
	ds_read_b128 v[208:211], v145 offset:53248
	ds_read_b128 v[212:215], v145 offset:55296
	ds_read_b128 v[164:167], v81 offset:16384
	ds_read_b128 v[168:171], v81 offset:18432
	ds_read_b128 v[174:177], v81 offset:20480
	ds_read_b128 v[182:185], v81 offset:22528
	s_waitcnt lgkmcnt(0)
	s_barrier
	s_add_i32 m0, s64, 0x0
	s_nop 0
	global_load_lds_dwordx4 v76, s[50:51]
	s_add_i32 m0, s64, 0x1000
	s_nop 0
	global_load_lds_dwordx4 v77, s[50:51]
	s_add_i32 m0, s64, 0x2000
	s_nop 0
	global_load_lds_dwordx4 v78, s[50:51]
	s_add_i32 m0, s64, 0x3000
	s_nop 0
	global_load_lds_dwordx4 v79, s[50:51]
	s_add_i32 m0, s64, 0x4000
	s_nop 0
	global_load_lds_dwordx4 v76, s[52:53]
	s_add_i32 m0, s64, 0x5000
	s_nop 0
	global_load_lds_dwordx4 v77, s[52:53]
	s_add_i32 m0, s64, 0x6000
	s_nop 0
	global_load_lds_dwordx4 v78, s[52:53]
	s_add_i32 m0, s64, 0x7000
	s_nop 0
	global_load_lds_dwordx4 v79, s[52:53]
	s_add_u32 s50, s50, 0x80
	s_addc_u32 s51, s51, 0
	s_add_u32 s52, s52, 0x80
	s_addc_u32 s53, s53, 0
	s_setprio 1
	v_mfma_f32_16x16x32_bf16 v[62:65], v[188:191], v[148:151], v[62:65]
	v_mfma_f32_16x16x32_bf16 v[54:57], v[192:195], v[148:151], v[54:57]
	v_mfma_f32_16x16x32_bf16 v[58:61], v[208:211], v[148:151], v[58:61]
	v_mfma_f32_16x16x32_bf16 v[50:53], v[212:215], v[148:151], v[50:53]
	v_mfma_f32_16x16x32_bf16 v[46:49], v[188:191], v[152:155], v[46:49]
	v_mfma_f32_16x16x32_bf16 v[38:41], v[192:195], v[152:155], v[38:41]
	v_mfma_f32_16x16x32_bf16 v[42:45], v[208:211], v[152:155], v[42:45]
	v_mfma_f32_16x16x32_bf16 v[34:37], v[212:215], v[152:155], v[34:37]
	v_mfma_f32_16x16x32_bf16 v[30:33], v[188:191], v[156:159], v[30:33]
	v_mfma_f32_16x16x32_bf16 v[22:25], v[192:195], v[156:159], v[22:25]
	v_mfma_f32_16x16x32_bf16 v[26:29], v[208:211], v[156:159], v[26:29]
	v_mfma_f32_16x16x32_bf16 v[18:21], v[212:215], v[156:159], v[18:21]
	v_mfma_f32_16x16x32_bf16 v[14:17], v[188:191], v[160:163], v[14:17]
	v_mfma_f32_16x16x32_bf16 v[6:9], v[192:195], v[160:163], v[6:9]
	v_mfma_f32_16x16x32_bf16 v[10:13], v[208:211], v[160:163], v[10:13]
	v_mfma_f32_16x16x32_bf16 v[2:5], v[212:215], v[160:163], v[2:5]
	v_mfma_f32_16x16x32_bf16 v[66:69], v[188:191], v[164:167], v[66:69]
	v_mfma_f32_16x16x32_bf16 v[70:73], v[192:195], v[164:167], v[70:73]
	v_mfma_f32_16x16x32_bf16 v[82:85], v[208:211], v[164:167], v[82:85]
	v_mfma_f32_16x16x32_bf16 v[86:89], v[212:215], v[164:167], v[86:89]
	v_mfma_f32_16x16x32_bf16 v[90:93], v[188:191], v[168:171], v[90:93]
	v_mfma_f32_16x16x32_bf16 v[94:97], v[192:195], v[168:171], v[94:97]
	v_mfma_f32_16x16x32_bf16 v[98:101], v[208:211], v[168:171], v[98:101]
	v_mfma_f32_16x16x32_bf16 v[102:105], v[212:215], v[168:171], v[102:105]
	v_mfma_f32_16x16x32_bf16 v[106:109], v[188:191], v[174:177], v[106:109]
	v_mfma_f32_16x16x32_bf16 v[110:113], v[192:195], v[174:177], v[110:113]
	v_mfma_f32_16x16x32_bf16 v[114:117], v[208:211], v[174:177], v[114:117]
	v_mfma_f32_16x16x32_bf16 v[118:121], v[212:215], v[174:177], v[118:121]
	v_mfma_f32_16x16x32_bf16 v[122:125], v[188:191], v[182:185], v[122:125]
	v_mfma_f32_16x16x32_bf16 v[126:129], v[192:195], v[182:185], v[126:129]
	v_mfma_f32_16x16x32_bf16 v[136:139], v[208:211], v[182:185], v[136:139]
	v_mfma_f32_16x16x32_bf16 v[140:143], v[212:215], v[182:185], v[140:143]
	s_setprio 0
	s_add_i32 s65, s65, -1
	s_cmp_lg_u32 s65, 0
	s_cbranch_scc1 .Lf2_k
	s_waitcnt vmcnt(0)
	s_barrier
	s_add_i32 m0, s64, 0xc000
	s_nop 0
	global_load_lds_dwordx4 v76, s[58:59]
	s_add_i32 m0, s64, 0xd000
	s_nop 0
	global_load_lds_dwordx4 v77, s[58:59]
	s_add_i32 m0, s64, 0xe000
	s_nop 0
	global_load_lds_dwordx4 v78, s[58:59]
	s_add_i32 m0, s64, 0xf000
	s_nop 0
	global_load_lds_dwordx4 v79, s[58:59]
	s_add_u32 s58, s58, 0x80
	s_addc_u32 s59, s59, 0
	ds_read_b128 v[148:151], v80 offset:0
	ds_read_b128 v[152:155], v80 offset:2048
	ds_read_b128 v[156:159], v80 offset:4096
	ds_read_b128 v[160:163], v80 offset:6144
	ds_read_b128 v[188:191], v144 offset:32768
	ds_read_b128 v[192:195], v144 offset:34816
	ds_read_b128 v[208:211], v144 offset:36864
	ds_read_b128 v[212:215], v144 offset:38912
	ds_read_b128 v[164:167], v80 offset:16384
	ds_read_b128 v[168:171], v80 offset:18432
	ds_read_b128 v[174:177], v80 offset:20480
	ds_read_b128 v[182:185], v80 offset:22528
	s_setprio 1
	s_waitcnt lgkmcnt(4)
	v_mfma_f32_16x16x32_bf16 v[62:65], v[188:191], v[148:151], v[62:65]
	v_mfma_f32_16x16x32_bf16 v[54:57], v[192:195], v[148:151], v[54:57]
	v_mfma_f32_16x16x32_bf16 v[58:61], v[208:211], v[148:151], v[58:61]
	v_mfma_f32_16x16x32_bf16 v[50:53], v[212:215], v[148:151], v[50:53]
	v_mfma_f32_16x16x32_bf16 v[46:49], v[188:191], v[152:155], v[46:49]
	v_mfma_f32_16x16x32_bf16 v[38:41], v[192:195], v[152:155], v[38:41]
	v_mfma_f32_16x16x32_bf16 v[42:45], v[208:211], v[152:155], v[42:45]
	v_mfma_f32_16x16x32_bf16 v[34:37], v[212:215], v[152:155], v[34:37]
	v_mfma_f32_16x16x32_bf16 v[30:33], v[188:191], v[156:159], v[30:33]
	v_mfma_f32_16x16x32_bf16 v[22:25], v[192:195], v[156:159], v[22:25]
	v_mfma_f32_16x16x32_bf16 v[26:29], v[208:211], v[156:159], v[26:29]
	v_mfma_f32_16x16x32_bf16 v[18:21], v[212:215], v[156:159], v[18:21]
	v_mfma_f32_16x16x32_bf16 v[14:17], v[188:191], v[160:163], v[14:17]
	v_mfma_f32_16x16x32_bf16 v[6:9], v[192:195], v[160:163], v[6:9]
	v_mfma_f32_16x16x32_bf16 v[10:13], v[208:211], v[160:163], v[10:13]
	v_mfma_f32_16x16x32_bf16 v[2:5], v[212:215], v[160:163], v[2:5]
	s_waitcnt lgkmcnt(0)
	v_mfma_f32_16x16x32_bf16 v[66:69], v[188:191], v[164:167], v[66:69]
	v_mfma_f32_16x16x32_bf16 v[70:73], v[192:195], v[164:167], v[70:73]
	v_mfma_f32_16x16x32_bf16 v[82:85], v[208:211], v[164:167], v[82:85]
	v_mfma_f32_16x16x32_bf16 v[86:89], v[212:215], v[164:167], v[86:89]
	v_mfma_f32_16x16x32_bf16 v[90:93], v[188:191], v[168:171], v[90:93]
	v_mfma_f32_16x16x32_bf16 v[94:97], v[192:195], v[168:171], v[94:97]
	v_mfma_f32_16x16x32_bf16 v[98:101], v[208:211], v[168:171], v[98:101]
	v_mfma_f32_16x16x32_bf16 v[102:105], v[212:215], v[168:171], v[102:105]
	v_mfma_f32_16x16x32_bf16 v[106:109], v[188:191], v[174:177], v[106:109]
	v_mfma_f32_16x16x32_bf16 v[110:113], v[192:195], v[174:177], v[110:113]
	v_mfma_f32_16x16x32_bf16 v[114:117], v[208:211], v[174:177], v[114:117]
	v_mfma_f32_16x16x32_bf16 v[118:121], v[212:215], v[174:177], v[118:121]
	v_mfma_f32_16x16x32_bf16 v[122:125], v[188:191], v[182:185], v[122:125]
	v_mfma_f32_16x16x32_bf16 v[126:129], v[192:195], v[182:185], v[126:129]
	v_mfma_f32_16x16x32_bf16 v[136:139], v[208:211], v[182:185], v[136:139]
	v_mfma_f32_16x16x32_bf16 v[140:143], v[212:215], v[182:185], v[140:143]
	s_setprio 0
	ds_read_b128 v[148:151], v81 offset:0
	ds_read_b128 v[152:155], v81 offset:2048
	ds_read_b128 v[156:159], v81 offset:4096
	ds_read_b128 v[160:163], v81 offset:6144
	ds_read_b128 v[188:191], v145 offset:32768
	ds_read_b128 v[192:195], v145 offset:34816
	ds_read_b128 v[208:211], v145 offset:36864
	ds_read_b128 v[212:215], v145 offset:38912
	ds_read_b128 v[164:167], v81 offset:16384
	ds_read_b128 v[168:171], v81 offset:18432
	ds_read_b128 v[174:177], v81 offset:20480
	ds_read_b128 v[182:185], v81 offset:22528
	s_waitcnt lgkmcnt(0)
	s_barrier
	s_add_i32 m0, s64, 0x0
	s_nop 0
	global_load_lds_dwordx4 v76, s[50:51]
	s_add_i32 m0, s64, 0x1000
	s_nop 0
	global_load_lds_dwordx4 v77, s[50:51]
	s_add_i32 m0, s64, 0x2000
	s_nop 0
	global_load_lds_dwordx4 v78, s[50:51]
	s_add_i32 m0, s64, 0x3000
	s_nop 0
	global_load_lds_dwordx4 v79, s[50:51]
	s_add_i32 m0, s64, 0x4000
	s_nop 0
	global_load_lds_dwordx4 v76, s[52:53]
	s_add_i32 m0, s64, 0x5000
	s_nop 0
	global_load_lds_dwordx4 v77, s[52:53]
	s_add_i32 m0, s64, 0x6000
	s_nop 0
	global_load_lds_dwordx4 v78, s[52:53]
	s_add_i32 m0, s64, 0x7000
	s_nop 0
	global_load_lds_dwordx4 v79, s[52:53]
	s_add_u32 s50, s50, 0x80
	s_addc_u32 s51, s51, 0
	s_add_u32 s52, s52, 0x80
	s_addc_u32 s53, s53, 0
	s_setprio 1
	v_mfma_f32_16x16x32_bf16 v[62:65], v[188:191], v[148:151], v[62:65]
	v_mfma_f32_16x16x32_bf16 v[54:57], v[192:195], v[148:151], v[54:57]
	v_mfma_f32_16x16x32_bf16 v[58:61], v[208:211], v[148:151], v[58:61]
	v_mfma_f32_16x16x32_bf16 v[50:53], v[212:215], v[148:151], v[50:53]
	v_mfma_f32_16x16x32_bf16 v[46:49], v[188:191], v[152:155], v[46:49]
	v_mfma_f32_16x16x32_bf16 v[38:41], v[192:195], v[152:155], v[38:41]
	v_mfma_f32_16x16x32_bf16 v[42:45], v[208:211], v[152:155], v[42:45]
	v_mfma_f32_16x16x32_bf16 v[34:37], v[212:215], v[152:155], v[34:37]
	v_mfma_f32_16x16x32_bf16 v[30:33], v[188:191], v[156:159], v[30:33]
	v_mfma_f32_16x16x32_bf16 v[22:25], v[192:195], v[156:159], v[22:25]
	v_mfma_f32_16x16x32_bf16 v[26:29], v[208:211], v[156:159], v[26:29]
	v_mfma_f32_16x16x32_bf16 v[18:21], v[212:215], v[156:159], v[18:21]
	v_mfma_f32_16x16x32_bf16 v[14:17], v[188:191], v[160:163], v[14:17]
	v_mfma_f32_16x16x32_bf16 v[6:9], v[192:195], v[160:163], v[6:9]
	v_mfma_f32_16x16x32_bf16 v[10:13], v[208:211], v[160:163], v[10:13]
	v_mfma_f32_16x16x32_bf16 v[2:5], v[212:215], v[160:163], v[2:5]
	v_mfma_f32_16x16x32_bf16 v[66:69], v[188:191], v[164:167], v[66:69]
	v_mfma_f32_16x16x32_bf16 v[70:73], v[192:195], v[164:167], v[70:73]
	v_mfma_f32_16x16x32_bf16 v[82:85], v[208:211], v[164:167], v[82:85]
	v_mfma_f32_16x16x32_bf16 v[86:89], v[212:215], v[164:167], v[86:89]
	v_mfma_f32_16x16x32_bf16 v[90:93], v[188:191], v[168:171], v[90:93]
	v_mfma_f32_16x16x32_bf16 v[94:97], v[192:195], v[168:171], v[94:97]
	v_mfma_f32_16x16x32_bf16 v[98:101], v[208:211], v[168:171], v[98:101]
	v_mfma_f32_16x16x32_bf16 v[102:105], v[212:215], v[168:171], v[102:105]
	v_mfma_f32_16x16x32_bf16 v[106:109], v[188:191], v[174:177], v[106:109]
	v_mfma_f32_16x16x32_bf16 v[110:113], v[192:195], v[174:177], v[110:113]
	v_mfma_f32_16x16x32_bf16 v[114:117], v[208:211], v[174:177], v[114:117]
	v_mfma_f32_16x16x32_bf16 v[118:121], v[212:215], v[174:177], v[118:121]
	v_mfma_f32_16x16x32_bf16 v[122:125], v[188:191], v[182:185], v[122:125]
	v_mfma_f32_16x16x32_bf16 v[126:129], v[192:195], v[182:185], v[126:129]
	v_mfma_f32_16x16x32_bf16 v[136:139], v[208:211], v[182:185], v[136:139]
	v_mfma_f32_16x16x32_bf16 v[140:143], v[212:215], v[182:185], v[140:143]
	s_setprio 0
	s_waitcnt vmcnt(0)
	s_barrier
	ds_read_b128 v[148:151], v80 offset:0
	ds_read_b128 v[152:155], v80 offset:2048
	ds_read_b128 v[156:159], v80 offset:4096
	ds_read_b128 v[160:163], v80 offset:6144
	ds_read_b128 v[188:191], v144 offset:49152
	ds_read_b128 v[192:195], v144 offset:51200
	ds_read_b128 v[208:211], v144 offset:53248
	ds_read_b128 v[212:215], v144 offset:55296
	ds_read_b128 v[164:167], v80 offset:16384
	ds_read_b128 v[168:171], v80 offset:18432
	ds_read_b128 v[174:177], v80 offset:20480
	ds_read_b128 v[182:185], v80 offset:22528
	s_setprio 1
	s_waitcnt lgkmcnt(4)
	v_mfma_f32_16x16x32_bf16 v[62:65], v[188:191], v[148:151], v[62:65]
	v_mfma_f32_16x16x32_bf16 v[54:57], v[192:195], v[148:151], v[54:57]
	v_mfma_f32_16x16x32_bf16 v[58:61], v[208:211], v[148:151], v[58:61]
	v_mfma_f32_16x16x32_bf16 v[50:53], v[212:215], v[148:151], v[50:53]
	v_mfma_f32_16x16x32_bf16 v[46:49], v[188:191], v[152:155], v[46:49]
	v_mfma_f32_16x16x32_bf16 v[38:41], v[192:195], v[152:155], v[38:41]
	v_mfma_f32_16x16x32_bf16 v[42:45], v[208:211], v[152:155], v[42:45]
	v_mfma_f32_16x16x32_bf16 v[34:37], v[212:215], v[152:155], v[34:37]
	v_mfma_f32_16x16x32_bf16 v[30:33], v[188:191], v[156:159], v[30:33]
	v_mfma_f32_16x16x32_bf16 v[22:25], v[192:195], v[156:159], v[22:25]
	v_mfma_f32_16x16x32_bf16 v[26:29], v[208:211], v[156:159], v[26:29]
	v_mfma_f32_16x16x32_bf16 v[18:21], v[212:215], v[156:159], v[18:21]
	v_mfma_f32_16x16x32_bf16 v[14:17], v[188:191], v[160:163], v[14:17]
	v_mfma_f32_16x16x32_bf16 v[6:9], v[192:195], v[160:163], v[6:9]
	v_mfma_f32_16x16x32_bf16 v[10:13], v[208:211], v[160:163], v[10:13]
	v_mfma_f32_16x16x32_bf16 v[2:5], v[212:215], v[160:163], v[2:5]
	s_waitcnt lgkmcnt(0)
	v_mfma_f32_16x16x32_bf16 v[66:69], v[188:191], v[164:167], v[66:69]
	v_mfma_f32_16x16x32_bf16 v[70:73], v[192:195], v[164:167], v[70:73]
	v_mfma_f32_16x16x32_bf16 v[82:85], v[208:211], v[164:167], v[82:85]
	v_mfma_f32_16x16x32_bf16 v[86:89], v[212:215], v[164:167], v[86:89]
	v_mfma_f32_16x16x32_bf16 v[90:93], v[188:191], v[168:171], v[90:93]
	v_mfma_f32_16x16x32_bf16 v[94:97], v[192:195], v[168:171], v[94:97]
	v_mfma_f32_16x16x32_bf16 v[98:101], v[208:211], v[168:171], v[98:101]
	v_mfma_f32_16x16x32_bf16 v[102:105], v[212:215], v[168:171], v[102:105]
	v_mfma_f32_16x16x32_bf16 v[106:109], v[188:191], v[174:177], v[106:109]
	v_mfma_f32_16x16x32_bf16 v[110:113], v[192:195], v[174:177], v[110:113]
	v_mfma_f32_16x16x32_bf16 v[114:117], v[208:211], v[174:177], v[114:117]
	v_mfma_f32_16x16x32_bf16 v[118:121], v[212:215], v[174:177], v[118:121]
	v_mfma_f32_16x16x32_bf16 v[122:125], v[188:191], v[182:185], v[122:125]
	v_mfma_f32_16x16x32_bf16 v[126:129], v[192:195], v[182:185], v[126:129]
	v_mfma_f32_16x16x32_bf16 v[136:139], v[208:211], v[182:185], v[136:139]
	v_mfma_f32_16x16x32_bf16 v[140:143], v[212:215], v[182:185], v[140:143]
	s_setprio 0
	ds_read_b128 v[148:151], v81 offset:0
	ds_read_b128 v[152:155], v81 offset:2048
	ds_read_b128 v[156:159], v81 offset:4096
	ds_read_b128 v[160:163], v81 offset:6144
	ds_read_b128 v[188:191], v145 offset:49152
	ds_read_b128 v[192:195], v145 offset:51200
	ds_read_b128 v[208:211], v145 offset:53248
	ds_read_b128 v[212:215], v145 offset:55296
	ds_read_b128 v[164:167], v81 offset:16384
	ds_read_b128 v[168:171], v81 offset:18432
	ds_read_b128 v[174:177], v81 offset:20480
	ds_read_b128 v[182:185], v81 offset:22528
	s_setprio 1
	s_waitcnt lgkmcnt(4)
	v_mfma_f32_16x16x32_bf16 v[62:65], v[188:191], v[148:151], v[62:65]
	v_mfma_f32_16x16x32_bf16 v[54:57], v[192:195], v[148:151], v[54:57]
	v_mfma_f32_16x16x32_bf16 v[58:61], v[208:211], v[148:151], v[58:61]
	v_mfma_f32_16x16x32_bf16 v[50:53], v[212:215], v[148:151], v[50:53]
	v_mfma_f32_16x16x32_bf16 v[46:49], v[188:191], v[152:155], v[46:49]
	v_mfma_f32_16x16x32_bf16 v[38:41], v[192:195], v[152:155], v[38:41]
	v_mfma_f32_16x16x32_bf16 v[42:45], v[208:211], v[152:155], v[42:45]
	v_mfma_f32_16x16x32_bf16 v[34:37], v[212:215], v[152:155], v[34:37]
	v_mfma_f32_16x16x32_bf16 v[30:33], v[188:191], v[156:159], v[30:33]
	v_mfma_f32_16x16x32_bf16 v[22:25], v[192:195], v[156:159], v[22:25]
	v_mfma_f32_16x16x32_bf16 v[26:29], v[208:211], v[156:159], v[26:29]
	v_mfma_f32_16x16x32_bf16 v[18:21], v[212:215], v[156:159], v[18:21]
	v_mfma_f32_16x16x32_bf16 v[14:17], v[188:191], v[160:163], v[14:17]
	v_mfma_f32_16x16x32_bf16 v[6:9], v[192:195], v[160:163], v[6:9]
	v_mfma_f32_16x16x32_bf16 v[10:13], v[208:211], v[160:163], v[10:13]
	v_mfma_f32_16x16x32_bf16 v[2:5], v[212:215], v[160:163], v[2:5]
	s_waitcnt lgkmcnt(0)
	v_mfma_f32_16x16x32_bf16 v[66:69], v[188:191], v[164:167], v[66:69]
	v_mfma_f32_16x16x32_bf16 v[70:73], v[192:195], v[164:167], v[70:73]
	v_mfma_f32_16x16x32_bf16 v[82:85], v[208:211], v[164:167], v[82:85]
	v_mfma_f32_16x16x32_bf16 v[86:89], v[212:215], v[164:167], v[86:89]
	v_mfma_f32_16x16x32_bf16 v[90:93], v[188:191], v[168:171], v[90:93]
	v_mfma_f32_16x16x32_bf16 v[94:97], v[192:195], v[168:171], v[94:97]
	v_mfma_f32_16x16x32_bf16 v[98:101], v[208:211], v[168:171], v[98:101]
	v_mfma_f32_16x16x32_bf16 v[102:105], v[212:215], v[168:171], v[102:105]
	v_mfma_f32_16x16x32_bf16 v[106:109], v[188:191], v[174:177], v[106:109]
	v_mfma_f32_16x16x32_bf16 v[110:113], v[192:195], v[174:177], v[110:113]
	v_mfma_f32_16x16x32_bf16 v[114:117], v[208:211], v[174:177], v[114:117]
	v_mfma_f32_16x16x32_bf16 v[118:121], v[212:215], v[174:177], v[118:121]
	v_mfma_f32_16x16x32_bf16 v[122:125], v[188:191], v[182:185], v[122:125]
	v_mfma_f32_16x16x32_bf16 v[126:129], v[192:195], v[182:185], v[126:129]
	v_mfma_f32_16x16x32_bf16 v[136:139], v[208:211], v[182:185], v[136:139]
	v_mfma_f32_16x16x32_bf16 v[140:143], v[212:215], v[182:185], v[140:143]
	s_setprio 0
	s_nop 7
	s_nop 7
	s_nop 7
	v_mov_b32_e32 v148, v66
	v_mov_b32_e32 v149, v67
	v_mov_b32_e32 v150, v68
	v_mov_b32_e32 v151, v69
	v_mov_b32_e32 v152, v70
	v_mov_b32_e32 v153, v71
	v_mov_b32_e32 v154, v72
	v_mov_b32_e32 v155, v73
	v_mov_b32_e32 v156, v82
	v_mov_b32_e32 v157, v83
	v_mov_b32_e32 v158, v84
	v_mov_b32_e32 v159, v85
	v_mov_b32_e32 v160, v86
	v_mov_b32_e32 v161, v87
	v_mov_b32_e32 v162, v88
	v_mov_b32_e32 v163, v89
	v_mov_b32_e32 v164, v90
	v_mov_b32_e32 v165, v91
	v_mov_b32_e32 v166, v92
	v_mov_b32_e32 v167, v93
	v_mov_b32_e32 v168, v94
	v_mov_b32_e32 v169, v95
	v_mov_b32_e32 v170, v96
	v_mov_b32_e32 v171, v97
	v_mov_b32_e32 v174, v98
	v_mov_b32_e32 v175, v99
	v_mov_b32_e32 v176, v100
	v_mov_b32_e32 v177, v101
	v_mov_b32_e32 v182, v102
	v_mov_b32_e32 v183, v103
	v_mov_b32_e32 v184, v104
	v_mov_b32_e32 v185, v105
	v_mov_b32_e32 v188, v106
	v_mov_b32_e32 v189, v107
	v_mov_b32_e32 v190, v108
	v_mov_b32_e32 v191, v109
	v_mov_b32_e32 v192, v110
	v_mov_b32_e32 v193, v111
	v_mov_b32_e32 v194, v112
	v_mov_b32_e32 v195, v113
	v_mov_b32_e32 v208, v114
	v_mov_b32_e32 v209, v115
	v_mov_b32_e32 v210, v116
	v_mov_b32_e32 v211, v117
	v_mov_b32_e32 v212, v118
	v_mov_b32_e32 v213, v119
	v_mov_b32_e32 v214, v120
	v_mov_b32_e32 v215, v121
	v_mov_b32_e32 v216, v122
	v_mov_b32_e32 v217, v123
	v_mov_b32_e32 v218, v124
	v_mov_b32_e32 v219, v125
	v_mov_b32_e32 v220, v126
	v_mov_b32_e32 v221, v127
	v_mov_b32_e32 v222, v128
	v_mov_b32_e32 v223, v129
	v_mov_b32_e32 v242, v136
	v_mov_b32_e32 v243, v137
	v_mov_b32_e32 v244, v138
	v_mov_b32_e32 v245, v139
	v_mov_b32_e32 v199, v140
	v_mov_b32_e32 v206, v141
	v_mov_b32_e32 v207, v142
	v_mov_b32_e32 v226, v143
	s_add_i32 s48, s48, 1
	s_mov_b32 s39, 0
	v_readlane_b32 s30, v249, 0
	s_nop 0
	s_and_b32 s31, s30, 7
	s_lshr_b32 s30, s30, 3
	s_cmp_lt_u32 s30, 32
	s_cselect_b32 s35, 6, 5
	s_cmp_lt_u32 s48, s35
	s_cbranch_scc0 .Lf2_c1_extra
	s_lshl_b32 s33, s48, 6
	s_add_i32 s33, s33, s30
	s_mov_b32 s34, 0
	s_cmp_ge_u32 s33, 0x58
	s_addc_u32 s34, s34, 0
	s_cmp_ge_u32 s33, 0xb0
	s_addc_u32 s34, s34, 0
	s_cmp_ge_u32 s33, 0x108
	s_addc_u32 s34, s34, 0
	s_mul_i32 s36, s34, 0x58
	s_sub_i32 s33, s33, s36
	s_lshr_b32 s37, s33, 1
	s_and_b32 s33, s33, 1
	s_lshl_b32 s34, s34, 2
	s_add_i32 s33, s33, s34
	s_lshl_b32 s33, s33, 3
	s_add_i32 s36, s33, s31
	s_add_i32 s38, s36, 16
	s_branch .Lf2_c1_have
